# attention work queue: the next item's atomic is issued at the head of the current item's epilogue (round trip hidden), counted vmcnt(8) at the consumer (on top of v34)
# baseline (speedup 1.0000x reference)
; #define LAS __attribute__((address_space(3)))
; __device__ __forceinline__ int fresh_tid() { int t; asm volatile("v_mov_b32 %0, %1" : "=v"(t) : "v"(threadIdx.x)); return t; }
; __device__ __forceinline__ int fresh_bid() { int t; asm volatile("s_mov_b32 %0, %1" : "=s"(t) : "s"(blockIdx.x)); return t; }
; __device__ __forceinline__ void phase_mix(const Ctx& a, int l, int b, LAS unsigned char* lds, int rep) {
;     unsigned* ctr = (unsigned*)(a.ws + WS_CTR) + ((l * 2 + b) * 2 + rep);
;     const bool do_scan = (rep == 0) || REP_MODE != 2, do_attn = (rep == 0) || REP_MODE != 1;
;     LAS int* sitem = (LAS int*)(lds + LDS_BYTES - 16);
;     if (do_scan && fresh_bid() < 16) gdn_scan_item(a, l, b, fresh_bid() >> 2, fresh_bid() & 3, lds, rep ? SCAN_VARIANT : 0);
;     if (do_attn) for (;;) {
;         if (fresh_tid() == 0) *sitem = (int)atomicAdd(ctr, 1u);
;         __syncthreads();
;         const int it = *sitem;
;         __syncthreads();
.LBB0_161:
	v_readlane_b32 s6, v255, 6
	s_or_b32 s46, s9, s6
	v_lshrrev_b32 v1, 6, v179
	s_nop 0
	v_readfirstlane_b32 s8, v1
	s_cmp_lg_u32 s8, 0
	s_cbranch_scc1 .Lq_init_done
	s_getreg_b32 s8, hwreg(HW_REG_XCC_ID, 0, 4)
	s_and_b32 s8, s8, 7
	v_mov_b32 v1, 0x23fe8
	v_mov_b32 v2, s8
	v_mov_b32 v3, 0
	ds_write_b64 v1, v[2:3]
	v_mov_b32 v214, 0
	s_waitcnt lgkmcnt(0)

; __device__ __forceinline__ int fresh_tid() { int t; asm volatile("v_mov_b32 %0, %1" : "=v"(t) : "v"(threadIdx.x)); return t; }
; __device__ __forceinline__ void phase_mix(const Ctx& a, int l, int b, LAS unsigned char* lds, int rep) {
;     ...
;     if (do_attn) for (;;) {
;         if (fresh_tid() == 0) *sitem = (int)atomicAdd(ctr, 1u);
;         __syncthreads();
;         const int it = *sitem;
;         __syncthreads();
;         if (it >= 512) break;
.LBB0_163:
	s_mov_b64 s[48:49], -1
	s_and_b64 vcc, exec, s[0:1]
	s_mov_b64 s[0:1], -1
	s_cbranch_vccz .LBB0_296
	v_lshrrev_b32 v1, 6, v179
	s_nop 0
	v_readfirstlane_b32 s8, v1
	s_cmp_lg_u32 s8, 0
	s_cbranch_scc1 .Lq_wait
	s_mov_b64 s[0:1], exec
	s_mov_b64 exec, 1
	v_mov_b32 v2, 0x23fe8
	ds_read_b64 v[4:5], v2
	s_add_u32 s38, s16, 0x58f0800
	s_addc_u32 s39, s17, 0
	s_waitcnt lgkmcnt(0)
	v_readfirstlane_b32 s36, v4
	v_readfirstlane_b32 s37, v5
	v_readfirstlane_b32 s8, v214
	s_cmp_eq_u32 s8, 1
	s_cbranch_scc0 .Lq_retry
	s_waitcnt vmcnt(8)
	v_mov_b32 v214, 0
	v_readfirstlane_b32 s9, v213
	s_cmp_lt_u32 s9, 64
	s_cbranch_scc1 .Lq_got
	s_branch .Lq_adv

; __device__ __forceinline__ int fresh_tid() { int t; asm volatile("v_mov_b32 %0, %1" : "=v"(t) : "v"(threadIdx.x)); return t; }
; __device__ __forceinline__ void phase_mix(const Ctx& a, int l, int b, LAS unsigned char* lds, int rep) {
;     ...
;     if (do_attn) for (;;) {
;         if (fresh_tid() == 0) *sitem = (int)atomicAdd(ctr, 1u);
;         __syncthreads();
;         const int it = *sitem;
;         __syncthreads();
;         if (it >= 512) break;
.Lq_adv:
	s_add_u32 s37, s37, 1
	s_add_u32 s36, s36, 1
	s_and_b32 s36, s36, 7
	s_cmp_lt_u32 s37, 8
	s_cbranch_scc1 .Lq_retry
	s_movk_i32 s12, 0x200
	s_branch .Lq_pub

; __device__ __forceinline__ int fresh_tid() { int t; asm volatile("v_mov_b32 %0, %1" : "=v"(t) : "v"(threadIdx.x)); return t; }
; __device__ __forceinline__ void phase_mix(const Ctx& a, int l, int b, LAS unsigned char* lds, int rep) {
;     ...
;     if (do_attn) for (;;) {
;         if (fresh_tid() == 0) *sitem = (int)atomicAdd(ctr, 1u);
;         __syncthreads();
.Lat0_epi:
	s_cmp_lg_u32 s51, 0
	s_cbranch_scc1 .Lat0_noq
	s_mov_b64 s[40:41], exec
	s_mov_b64 exec, 1
	v_mov_b32 v215, 0x23fe8
	ds_read_b32 v215, v215
	s_waitcnt lgkmcnt(0)
	v_readfirstlane_b32 s8, v215
	s_lshr_b32 s9, s46, 1
	s_lshl_b32 s9, s9, 3
	s_add_u32 s8, s8, s9
	s_and_b32 s9, s46, 1
	s_lshl_b32 s9, s9, 5
	s_add_u32 s8, s8, s9
	s_add_u32 s8, s8, 8
	s_lshl_b32 s8, s8, 2
	v_mov_b32 v216, s8
	s_add_u32 s56, s16, 0x58f0800
	s_addc_u32 s57, s17, 0
	v_mov_b32 v213, 1
	global_atomic_add v213, v216, v213, s[56:57] sc0
	v_mov_b32 v214, 1
	s_mov_b64 exec, s[40:41]
